# attention loops: row-sum accumulators start from the first pair instead of adding zero
# speedup vs baseline: 1.0003x; 1.0003x over previous
; DI unsigned pk2(float a, float b) { hwf32x2 f = {a, b}; hwbf16x2 r = __builtin_convertvector(f, hwbf16x2); return __builtin_bit_cast(unsigned, r); }
; #define MFMA32(a, b, c) __builtin_amdgcn_mfma_f32_32x32x16_bf16((a), (b), (c), 0, 0, 0)
; template <int MODE>
; DI void attn_mfma(const Params& p, int l, int b, int hd, int qb, unsigned char* smem) {
;     ...
;     float mx = -1e30f;
; #pragma unroll
;     for (int mt = 0; mt < 2; ++mt)
; #pragma unroll
;       for (int i = 0; i < 16; ++i) mx = fmaxf(mx, S[mt][i]);
;     mx = fmaxf(mx, __shfl_xor(mx, 32));
;     const float zmx = mx * cexp;
;     if (__any(zmx > mrun + 8.f)) {
;       const float mnew = fmaxf(mrun, zmx);
;       const float alpha = __builtin_amdgcn_exp2f(mrun - mnew);
;       mrun = mnew;
;       lsum *= alpha;
;       const f32x2 al2 = {alpha, alpha};
; #pragma unroll
;       for (int vt = 0; vt < 2; ++vt)
; #pragma unroll
;         for (int i = 0; i < 8; ++i) {
;           f32x2 o = {O[vt][2 * i], O[vt][2 * i + 1]};
;           o = o * al2;
;           O[vt][2 * i] = o.x; O[vt][2 * i + 1] = o.y;
;         }
;     }
;     const f32x2 c2 = {cexp, cexp}, m2 = {mrun, mrun};
;     f32x2 ps2 = {0.f, 0.f};
;     unsigned pk[2][8];
; #pragma unroll
;     for (int mt = 0; mt < 2; ++mt)
; #pragma unroll
;       for (int i = 0; i < 8; ++i) {
;         f32x2 z = {S[mt][2 * i], S[mt][2 * i + 1]};
;         z = z * c2 - m2;
;         f32x2 pv = {__builtin_amdgcn_exp2f(z.x), __builtin_amdgcn_exp2f(z.y)};
;         ps2 = ps2 + pv;
;         pk[mt][i] = pk2(pv.x, pv.y);
;       }
;     lsum += ps2.x + ps2.y;
; #pragma unroll
;     for (int mt = 0; mt < 2; ++mt)
; #pragma unroll
;       for (int s = 0; s < 2; ++s) {
;         const uint4 pu = make_uint4(pk[mt][4 * s], pk[mt][4 * s + 1], pk[mt][4 * s + 2], pk[mt][4 * s + 3]);
;         const bf16x8 pf = __builtin_bit_cast(bf16x8, pu);
; #pragma unroll
;         for (int vt = 0; vt < 2; ++vt) {
;           const unsigned char* bp = sVc + (vt * 32 + r) * 136 + (mt * 32 + 16 * s + 4 * h2) * 2;
;           const uint2 lo = *(const uint2*)(bp);
;           const uint2 hi = *(const uint2*)(bp + 16);
;           const uint4 u = make_uint4(lo.x, lo.y, hi.x, hi.y);
;           O[vt] = MFMA32(__builtin_bit_cast(bf16x8, u), pf, O[vt]);
;         }
;       }
.Laa_nra:
	v_fma_f32 v80, v80, s8, -v140
	v_fma_f32 v81, v81, s8, -v140
	v_fma_f32 v82, v82, s8, -v140
	v_fma_f32 v83, v83, s8, -v140
	v_fma_f32 v84, v84, s8, -v140
	v_fma_f32 v85, v85, s8, -v140
	v_fma_f32 v86, v86, s8, -v140
	v_fma_f32 v87, v87, s8, -v140
	v_exp_f32_e32 v80, v80
	v_exp_f32_e32 v81, v81
	v_exp_f32_e32 v82, v82
	v_exp_f32_e32 v83, v83
	v_exp_f32_e32 v84, v84
	v_exp_f32_e32 v85, v85
	v_exp_f32_e32 v86, v86
	v_exp_f32_e32 v87, v87
	v_add_f32_e32 v148, v82, v80
	v_add_f32_e32 v149, v83, v81
	v_add_f32_e32 v148, v84, v148
	v_add_f32_e32 v149, v85, v149
	v_add_f32_e32 v148, v86, v148
	v_add_f32_e32 v149, v87, v149
	v_cvt_pk_bf16_f32 v80, v80, v81
	v_cvt_pk_bf16_f32 v81, v82, v83
	v_cvt_pk_bf16_f32 v82, v84, v85
	v_cvt_pk_bf16_f32 v83, v86, v87
	v_fma_f32 v88, v88, s8, -v140
	v_fma_f32 v89, v89, s8, -v140
	v_fma_f32 v90, v90, s8, -v140
	v_mfma_f32_32x32x16_bf16 v[16:31], v[204:207], v[80:83], v[16:31]
	v_fma_f32 v91, v91, s8, -v140
	v_fma_f32 v92, v92, s8, -v140
	v_fma_f32 v93, v93, s8, -v140
	v_fma_f32 v94, v94, s8, -v140
	v_fma_f32 v95, v95, s8, -v140
	v_exp_f32_e32 v88, v88
	v_exp_f32_e32 v89, v89
	v_exp_f32_e32 v90, v90
	v_exp_f32_e32 v91, v91
	v_exp_f32_e32 v92, v92
	v_exp_f32_e32 v93, v93
	v_exp_f32_e32 v94, v94
	v_mfma_f32_32x32x16_bf16 v[0:15], v[208:211], v[80:83], v[0:15]
	v_exp_f32_e32 v95, v95
	v_add_f32_e32 v148, v88, v148
	v_add_f32_e32 v149, v89, v149
	v_add_f32_e32 v148, v90, v148
	v_add_f32_e32 v149, v91, v149
	v_add_f32_e32 v148, v92, v148
	v_add_f32_e32 v149, v93, v149
	v_add_f32_e32 v148, v94, v148
	v_add_f32_e32 v149, v95, v149
	v_cvt_pk_bf16_f32 v88, v88, v89
	v_cvt_pk_bf16_f32 v89, v90, v91
	v_cvt_pk_bf16_f32 v90, v92, v93
	v_cvt_pk_bf16_f32 v91, v94, v95
	v_fma_f32 v64, v64, s8, -v140
	v_fma_f32 v65, v65, s8, -v140
	v_fma_f32 v66, v66, s8, -v140
	v_mfma_f32_32x32x16_bf16 v[16:31], v[212:215], v[88:91], v[16:31]
	v_fma_f32 v67, v67, s8, -v140
	v_fma_f32 v68, v68, s8, -v140
	v_fma_f32 v69, v69, s8, -v140
	v_fma_f32 v70, v70, s8, -v140
	v_fma_f32 v71, v71, s8, -v140
	v_exp_f32_e32 v64, v64
	v_exp_f32_e32 v65, v65
	v_exp_f32_e32 v66, v66
	v_exp_f32_e32 v67, v67
	v_exp_f32_e32 v68, v68
	v_exp_f32_e32 v69, v69
	v_exp_f32_e32 v70, v70
	v_mfma_f32_32x32x16_bf16 v[0:15], v[216:219], v[88:91], v[0:15]
	v_exp_f32_e32 v71, v71
	v_add_f32_e32 v148, v64, v148
	v_add_f32_e32 v149, v65, v149
	v_add_f32_e32 v148, v66, v148
	v_add_f32_e32 v149, v67, v149
	v_add_f32_e32 v148, v68, v148
	v_add_f32_e32 v149, v69, v149
	v_add_f32_e32 v148, v70, v148
	v_add_f32_e32 v149, v71, v149
	v_cvt_pk_bf16_f32 v84, v64, v65
	v_cvt_pk_bf16_f32 v85, v66, v67
	v_cvt_pk_bf16_f32 v86, v68, v69
	v_cvt_pk_bf16_f32 v87, v70, v71
	v_fma_f32 v72, v72, s8, -v140
	v_fma_f32 v73, v73, s8, -v140
	v_fma_f32 v74, v74, s8, -v140
	s_waitcnt lgkmcnt(0)
	v_mfma_f32_32x32x16_bf16 v[16:31], v[220:223], v[84:87], v[16:31]
	v_fma_f32 v75, v75, s8, -v140
	v_fma_f32 v76, v76, s8, -v140
	v_fma_f32 v77, v77, s8, -v140
	v_fma_f32 v78, v78, s8, -v140
	v_fma_f32 v79, v79, s8, -v140
	v_exp_f32_e32 v72, v72
	v_exp_f32_e32 v73, v73
	v_exp_f32_e32 v74, v74
	v_exp_f32_e32 v75, v75
	v_exp_f32_e32 v76, v76
	v_exp_f32_e32 v77, v77
	v_exp_f32_e32 v78, v78
	v_mfma_f32_32x32x16_bf16 v[0:15], v[224:227], v[84:87], v[0:15]
	v_exp_f32_e32 v79, v79
	v_add_f32_e32 v148, v72, v148
	v_add_f32_e32 v149, v73, v149
	v_add_f32_e32 v148, v74, v148
	v_add_f32_e32 v149, v75, v149
	v_add_f32_e32 v148, v76, v148
	v_add_f32_e32 v149, v77, v149
	v_add_f32_e32 v148, v78, v148
	v_add_f32_e32 v149, v79, v149
	v_cvt_pk_bf16_f32 v64, v72, v73
	v_cvt_pk_bf16_f32 v65, v74, v75
	v_cvt_pk_bf16_f32 v66, v76, v77
	v_cvt_pk_bf16_f32 v67, v78, v79
	v_add_f32_e32 v151, v148, v149
	v_add_f32_e32 v152, v200, v151
	v_mfma_f32_32x32x16_bf16 v[16:31], v[228:231], v[64:67], v[16:31]
	v_max3_f32 v150, v48, s5, v49
	v_max3_f32 v150, v150, v50, v51
	v_max3_f32 v150, v150, v52, v53
	v_max3_f32 v150, v150, v54, v55
	v_max3_f32 v150, v150, v56, v57
	v_max3_f32 v150, v150, v58, v59
	v_max3_f32 v150, v150, v60, v61
	v_max3_f32 v150, v150, v62, v63
	v_mfma_f32_32x32x16_bf16 v[0:15], v[232:235], v[64:67], v[0:15]
	v_max3_f32 v150, v150, v32, v33
	v_max3_f32 v150, v150, v34, v35
	v_max3_f32 v150, v150, v36, v37
	v_max3_f32 v150, v150, v38, v39
	v_max3_f32 v150, v150, v40, v41
	v_max3_f32 v150, v150, v42, v43
	v_max3_f32 v150, v150, v44, v45
	v_max3_f32 v150, v150, v46, v47
	ds_bpermute_b32 v151, v170, v150
	ds_read2_b64 v[204:207], v238 offset0:64 offset1:66
	ds_read2_b64 v[208:211], v239 offset0:96 offset1:98
	ds_read2_b64 v[212:215], v238 offset0:68 offset1:70
	ds_read2_b64 v[216:219], v239 offset0:100 offset1:102
	ds_read2_b64 v[220:223], v238 offset0:72 offset1:74
	ds_read2_b64 v[224:227], v239 offset0:104 offset1:106
	ds_read2_b64 v[228:231], v238 offset0:76 offset1:78
	ds_read2_b64 v[232:235], v239 offset0:108 offset1:110
	s_waitcnt lgkmcnt(8)
	v_max_f32_e32 v151, v151, v151
	v_max_f32_e32 v150, v150, v151
	v_mul_f32_e32 v150, 0x3e8293ee, v150
	v_cmp_gt_f32_e32 vcc, v150, v146
	s_cbranch_vccz .Laa_nrb
	v_max_f32_e32 v150, v150, v150
	v_max_f32_e32 v151, v140, v140
	v_max_f32_e32 v150, v151, v150
	v_sub_f32_e32 v151, v140, v150
	v_exp_f32_e32 v154, v151
	v_mov_b32_e32 v140, v150
	v_pk_mul_f32 v[16:17], v[16:17], v[154:155] op_sel_hi:[1,0]
	v_pk_mul_f32 v[18:19], v[18:19], v[154:155] op_sel_hi:[1,0]
	v_pk_mul_f32 v[20:21], v[20:21], v[154:155] op_sel_hi:[1,0]
	v_pk_mul_f32 v[22:23], v[22:23], v[154:155] op_sel_hi:[1,0]
	v_pk_mul_f32 v[24:25], v[24:25], v[154:155] op_sel_hi:[1,0]
	v_pk_mul_f32 v[26:27], v[26:27], v[154:155] op_sel_hi:[1,0]
	v_pk_mul_f32 v[28:29], v[28:29], v[154:155] op_sel_hi:[1,0]
	v_pk_mul_f32 v[30:31], v[30:31], v[154:155] op_sel_hi:[1,0]
	v_pk_mul_f32 v[0:1], v[0:1], v[154:155] op_sel_hi:[1,0]
	v_pk_mul_f32 v[2:3], v[2:3], v[154:155] op_sel_hi:[1,0]
	v_pk_mul_f32 v[4:5], v[4:5], v[154:155] op_sel_hi:[1,0]
	v_pk_mul_f32 v[6:7], v[6:7], v[154:155] op_sel_hi:[1,0]
	v_pk_mul_f32 v[8:9], v[8:9], v[154:155] op_sel_hi:[1,0]
	v_pk_mul_f32 v[10:11], v[10:11], v[154:155] op_sel_hi:[1,0]
	v_pk_mul_f32 v[12:13], v[12:13], v[154:155] op_sel_hi:[1,0]
	v_pk_mul_f32 v[14:15], v[14:15], v[154:155] op_sel_hi:[1,0]
	v_mul_f32_e32 v152, v152, v154
; DI unsigned pk2(float a, float b) { hwf32x2 f = {a, b}; hwbf16x2 r = __builtin_convertvector(f, hwbf16x2); return __builtin_bit_cast(unsigned, r); }
; #define MFMA32(a, b, c) __builtin_amdgcn_mfma_f32_32x32x16_bf16((a), (b), (c), 0, 0, 0)
; template <int MODE>
; DI void attn_mfma(const Params& p, int l, int b, int hd, int qb, unsigned char* smem) {
;     ...
;     const f32x2 c2 = {cexp, cexp}, m2 = {mrun, mrun};
;     f32x2 ps2 = {0.f, 0.f};
;     unsigned pk[2][8];
; #pragma unroll
;     for (int mt = 0; mt < 2; ++mt)
; #pragma unroll
;       for (int i = 0; i < 8; ++i) {
;         f32x2 z = {S[mt][2 * i], S[mt][2 * i + 1]};
;         z = z * c2 - m2;
;         f32x2 pv = {__builtin_amdgcn_exp2f(z.x), __builtin_amdgcn_exp2f(z.y)};
;         ps2 = ps2 + pv;
;         pk[mt][i] = pk2(pv.x, pv.y);
;       }
;     lsum += ps2.x + ps2.y;
; #pragma unroll
;     for (int mt = 0; mt < 2; ++mt)
; #pragma unroll
;       for (int s = 0; s < 2; ++s) {
;         const uint4 pu = make_uint4(pk[mt][4 * s], pk[mt][4 * s + 1], pk[mt][4 * s + 2], pk[mt][4 * s + 3]);
;         const bf16x8 pf = __builtin_bit_cast(bf16x8, pu);
; #pragma unroll
;         for (int vt = 0; vt < 2; ++vt) {
;           const unsigned char* bp = sVc + (vt * 32 + r) * 136 + (mt * 32 + 16 * s + 4 * h2) * 2;
;           const uint2 lo = *(const uint2*)(bp);
;           const uint2 hi = *(const uint2*)(bp + 16);
;           const uint4 u = make_uint4(lo.x, lo.y, hi.x, hi.y);
;           O[vt] = MFMA32(__builtin_bit_cast(bf16x8, u), pf, O[vt]);
;         }
;       }
;     }
;   }
.Laa_nrb:
	v_fma_f32 v48, v48, s8, -v140
	v_fma_f32 v49, v49, s8, -v140
	v_fma_f32 v50, v50, s8, -v140
	v_fma_f32 v51, v51, s8, -v140
	v_fma_f32 v52, v52, s8, -v140
	v_fma_f32 v53, v53, s8, -v140
	v_fma_f32 v54, v54, s8, -v140
	v_fma_f32 v55, v55, s8, -v140
	v_exp_f32_e32 v48, v48
	v_exp_f32_e32 v49, v49
	v_exp_f32_e32 v50, v50
	v_exp_f32_e32 v51, v51
	v_exp_f32_e32 v52, v52
	v_exp_f32_e32 v53, v53
	v_exp_f32_e32 v54, v54
	v_exp_f32_e32 v55, v55
	v_add_f32_e32 v148, v50, v48
	v_add_f32_e32 v149, v51, v49
	v_add_f32_e32 v148, v52, v148
	v_add_f32_e32 v149, v53, v149
	v_add_f32_e32 v148, v54, v148
	v_add_f32_e32 v149, v55, v149
	v_cvt_pk_bf16_f32 v48, v48, v49
	v_cvt_pk_bf16_f32 v49, v50, v51
	v_cvt_pk_bf16_f32 v50, v52, v53
	v_cvt_pk_bf16_f32 v51, v54, v55
	v_fma_f32 v56, v56, s8, -v140
	v_fma_f32 v57, v57, s8, -v140
	v_fma_f32 v58, v58, s8, -v140
	s_waitcnt lgkmcnt(4)
	v_mfma_f32_32x32x16_bf16 v[16:31], v[204:207], v[48:51], v[16:31]
	v_fma_f32 v59, v59, s8, -v140
	v_fma_f32 v60, v60, s8, -v140
	v_fma_f32 v61, v61, s8, -v140
	v_fma_f32 v62, v62, s8, -v140
	v_fma_f32 v63, v63, s8, -v140
	v_exp_f32_e32 v56, v56
	v_exp_f32_e32 v57, v57
	v_exp_f32_e32 v58, v58
	v_exp_f32_e32 v59, v59
	v_exp_f32_e32 v60, v60
	v_exp_f32_e32 v61, v61
	v_exp_f32_e32 v62, v62
	v_mfma_f32_32x32x16_bf16 v[0:15], v[208:211], v[48:51], v[0:15]
	v_exp_f32_e32 v63, v63
	v_add_f32_e32 v148, v56, v148
	v_add_f32_e32 v149, v57, v149
	v_add_f32_e32 v148, v58, v148
	v_add_f32_e32 v149, v59, v149
	v_add_f32_e32 v148, v60, v148
	v_add_f32_e32 v149, v61, v149
	v_add_f32_e32 v148, v62, v148
	v_add_f32_e32 v149, v63, v149
	v_cvt_pk_bf16_f32 v56, v56, v57
	v_cvt_pk_bf16_f32 v57, v58, v59
	v_cvt_pk_bf16_f32 v58, v60, v61
	v_cvt_pk_bf16_f32 v59, v62, v63
	v_fma_f32 v32, v32, s8, -v140
	v_fma_f32 v33, v33, s8, -v140
	v_fma_f32 v34, v34, s8, -v140
	v_mfma_f32_32x32x16_bf16 v[16:31], v[212:215], v[56:59], v[16:31]
	v_fma_f32 v35, v35, s8, -v140
	v_fma_f32 v36, v36, s8, -v140
	v_fma_f32 v37, v37, s8, -v140
	v_fma_f32 v38, v38, s8, -v140
	v_fma_f32 v39, v39, s8, -v140
	v_exp_f32_e32 v32, v32
	v_exp_f32_e32 v33, v33
	v_exp_f32_e32 v34, v34
	v_exp_f32_e32 v35, v35
	v_exp_f32_e32 v36, v36
	v_exp_f32_e32 v37, v37
	v_exp_f32_e32 v38, v38
	v_mfma_f32_32x32x16_bf16 v[0:15], v[216:219], v[56:59], v[0:15]
	v_exp_f32_e32 v39, v39
	v_add_f32_e32 v148, v32, v148
	v_add_f32_e32 v149, v33, v149
	v_add_f32_e32 v148, v34, v148
	v_add_f32_e32 v149, v35, v149
	v_add_f32_e32 v148, v36, v148
	v_add_f32_e32 v149, v37, v149
	v_add_f32_e32 v148, v38, v148
	v_add_f32_e32 v149, v39, v149
	v_cvt_pk_bf16_f32 v52, v32, v33
	v_cvt_pk_bf16_f32 v53, v34, v35
	v_cvt_pk_bf16_f32 v54, v36, v37
	v_cvt_pk_bf16_f32 v55, v38, v39
	v_fma_f32 v40, v40, s8, -v140
	v_fma_f32 v41, v41, s8, -v140
	v_fma_f32 v42, v42, s8, -v140
	s_waitcnt lgkmcnt(0)
	v_mfma_f32_32x32x16_bf16 v[16:31], v[220:223], v[52:55], v[16:31]
	v_fma_f32 v43, v43, s8, -v140
	v_fma_f32 v44, v44, s8, -v140
	v_fma_f32 v45, v45, s8, -v140
	v_fma_f32 v46, v46, s8, -v140
	v_fma_f32 v47, v47, s8, -v140
	v_exp_f32_e32 v40, v40
	v_exp_f32_e32 v41, v41
	v_exp_f32_e32 v42, v42
	v_exp_f32_e32 v43, v43
	v_exp_f32_e32 v44, v44
	v_exp_f32_e32 v45, v45
	v_exp_f32_e32 v46, v46
	v_mfma_f32_32x32x16_bf16 v[0:15], v[224:227], v[52:55], v[0:15]
	v_exp_f32_e32 v47, v47
	v_add_f32_e32 v148, v40, v148
	v_add_f32_e32 v149, v41, v149
	v_add_f32_e32 v148, v42, v148
	v_add_f32_e32 v149, v43, v149
	v_add_f32_e32 v148, v44, v148
	v_add_f32_e32 v149, v45, v149
	v_add_f32_e32 v148, v46, v148
	v_add_f32_e32 v149, v47, v149
	v_cvt_pk_bf16_f32 v32, v40, v41
	v_cvt_pk_bf16_f32 v33, v42, v43
	v_cvt_pk_bf16_f32 v34, v44, v45
	v_cvt_pk_bf16_f32 v35, v46, v47
	v_add_f32_e32 v151, v148, v149
	v_add_f32_e32 v200, v152, v151
	v_mfma_f32_32x32x16_bf16 v[16:31], v[228:231], v[32:35], v[16:31]
	s_add_u32 s12, s12, 0x100
	s_addc_u32 s13, s13, 0
	s_add_u32 s10, s10, 0x111000
	s_addc_u32 s11, s11, 0
	v_mfma_f32_32x32x16_bf16 v[0:15], v[232:235], v[32:35], v[0:15]
	s_and_b64 vcc, exec, s[0:1]
	s_cbranch_vccz .LBB0_580

; DI unsigned pk2(float a, float b) { hwf32x2 f = {a, b}; hwbf16x2 r = __builtin_convertvector(f, hwbf16x2); return __builtin_bit_cast(unsigned, r); }
; #define MFMA32(a, b, c) __builtin_amdgcn_mfma_f32_32x32x16_bf16((a), (b), (c), 0, 0, 0)
; template <int MODE>
; DI void attn_mfma(const Params& p, int l, int b, int hd, int qb, unsigned char* smem) {
;     ...
;     const f32x2 c2 = {cexp, cexp}, m2 = {mrun, mrun};
;     f32x2 ps2 = {0.f, 0.f};
;     unsigned pk[2][8];
; #pragma unroll
;     for (int mt = 0; mt < 2; ++mt)
; #pragma unroll
;       for (int i = 0; i < 8; ++i) {
;         f32x2 z = {S[mt][2 * i], S[mt][2 * i + 1]};
;         z = z * c2 - m2;
;         f32x2 pv = {__builtin_amdgcn_exp2f(z.x), __builtin_amdgcn_exp2f(z.y)};
;         ps2 = ps2 + pv;
;         pk[mt][i] = pk2(pv.x, pv.y);
;       }
;     lsum += ps2.x + ps2.y;
; #pragma unroll
;     for (int mt = 0; mt < 2; ++mt)
; #pragma unroll
;       for (int s = 0; s < 2; ++s) {
;         const uint4 pu = make_uint4(pk[mt][4 * s], pk[mt][4 * s + 1], pk[mt][4 * s + 2], pk[mt][4 * s + 3]);
;         const bf16x8 pf = __builtin_bit_cast(bf16x8, pu);
; #pragma unroll
;         for (int vt = 0; vt < 2; ++vt) {
;           const unsigned char* bp = sVc + (vt * 32 + r) * 136 + (mt * 32 + 16 * s + 4 * h2) * 2;
;           const uint2 lo = *(const uint2*)(bp);
;           const uint2 hi = *(const uint2*)(bp + 16);
;           const uint4 u = make_uint4(lo.x, lo.y, hi.x, hi.y);
;           O[vt] = MFMA32(__builtin_bit_cast(bf16x8, u), pf, O[vt]);
;         }
;       }
.Lcc_nra:
	v_fma_f32 v80, v80, s28, -v166
	v_fma_f32 v81, v81, s28, -v166
	v_fma_f32 v82, v82, s28, -v166
	v_fma_f32 v83, v83, s28, -v166
	v_fma_f32 v84, v84, s28, -v166
	v_fma_f32 v85, v85, s28, -v166
	v_fma_f32 v86, v86, s28, -v166
	v_fma_f32 v87, v87, s28, -v166
	v_exp_f32_e32 v80, v80
	v_exp_f32_e32 v81, v81
	v_exp_f32_e32 v82, v82
	v_exp_f32_e32 v83, v83
	v_exp_f32_e32 v84, v84
	v_exp_f32_e32 v85, v85
	v_exp_f32_e32 v86, v86
	v_exp_f32_e32 v87, v87
	v_add_f32_e32 v208, v82, v80
	v_add_f32_e32 v209, v83, v81
	v_add_f32_e32 v208, v84, v208
	v_add_f32_e32 v209, v85, v209
	v_add_f32_e32 v208, v86, v208
	v_add_f32_e32 v209, v87, v209
	v_cvt_pk_bf16_f32 v80, v80, v81
	v_cvt_pk_bf16_f32 v81, v82, v83
	v_cvt_pk_bf16_f32 v82, v84, v85
	v_cvt_pk_bf16_f32 v83, v86, v87
	v_fma_f32 v88, v88, s28, -v166
	v_fma_f32 v89, v89, s28, -v166
	v_fma_f32 v90, v90, s28, -v166
	v_mfma_f32_32x32x16_bf16 v[16:31], v[220:223], v[80:83], v[16:31]
	v_fma_f32 v91, v91, s28, -v166
	v_fma_f32 v92, v92, s28, -v166
	v_fma_f32 v93, v93, s28, -v166
	v_fma_f32 v94, v94, s28, -v166
	v_fma_f32 v95, v95, s28, -v166
	v_exp_f32_e32 v88, v88
	v_exp_f32_e32 v89, v89
	v_exp_f32_e32 v90, v90
	v_exp_f32_e32 v91, v91
	v_exp_f32_e32 v92, v92
	v_exp_f32_e32 v93, v93
	v_exp_f32_e32 v94, v94
	v_mfma_f32_32x32x16_bf16 v[0:15], v[224:227], v[80:83], v[0:15]
	v_exp_f32_e32 v95, v95
	v_add_f32_e32 v208, v88, v208
	v_add_f32_e32 v209, v89, v209
	v_add_f32_e32 v208, v90, v208
	v_add_f32_e32 v209, v91, v209
	v_add_f32_e32 v208, v92, v208
	v_add_f32_e32 v209, v93, v209
	v_add_f32_e32 v208, v94, v208
	v_add_f32_e32 v209, v95, v209
	v_cvt_pk_bf16_f32 v88, v88, v89
	v_cvt_pk_bf16_f32 v89, v90, v91
	v_cvt_pk_bf16_f32 v90, v92, v93
	v_cvt_pk_bf16_f32 v91, v94, v95
	v_fma_f32 v64, v64, s28, -v166
	v_fma_f32 v65, v65, s28, -v166
	v_fma_f32 v66, v66, s28, -v166
	v_mfma_f32_32x32x16_bf16 v[16:31], v[228:231], v[88:91], v[16:31]
	v_fma_f32 v67, v67, s28, -v166
	v_fma_f32 v68, v68, s28, -v166
	v_fma_f32 v69, v69, s28, -v166
	v_fma_f32 v70, v70, s28, -v166
	v_fma_f32 v71, v71, s28, -v166
	v_exp_f32_e32 v64, v64
	v_exp_f32_e32 v65, v65
	v_exp_f32_e32 v66, v66
	v_exp_f32_e32 v67, v67
	v_exp_f32_e32 v68, v68
	v_exp_f32_e32 v69, v69
	v_exp_f32_e32 v70, v70
	v_mfma_f32_32x32x16_bf16 v[0:15], v[232:235], v[88:91], v[0:15]
	v_exp_f32_e32 v71, v71
	v_add_f32_e32 v208, v64, v208
	v_add_f32_e32 v209, v65, v209
	v_add_f32_e32 v208, v66, v208
	v_add_f32_e32 v209, v67, v209
	v_add_f32_e32 v208, v68, v208
	v_add_f32_e32 v209, v69, v209
	v_add_f32_e32 v208, v70, v208
	v_add_f32_e32 v209, v71, v209
	v_cvt_pk_bf16_f32 v84, v64, v65
	v_cvt_pk_bf16_f32 v85, v66, v67
	v_cvt_pk_bf16_f32 v86, v68, v69
	v_cvt_pk_bf16_f32 v87, v70, v71
	v_fma_f32 v72, v72, s28, -v166
	v_fma_f32 v73, v73, s28, -v166
	v_fma_f32 v74, v74, s28, -v166
	v_mfma_f32_32x32x16_bf16 v[16:31], v[236:239], v[84:87], v[16:31]
	v_fma_f32 v75, v75, s28, -v166
	v_fma_f32 v76, v76, s28, -v166
	v_fma_f32 v77, v77, s28, -v166
	v_fma_f32 v78, v78, s28, -v166
	v_fma_f32 v79, v79, s28, -v166
	v_exp_f32_e32 v72, v72
	v_exp_f32_e32 v73, v73
	v_exp_f32_e32 v74, v74
	v_exp_f32_e32 v75, v75
	v_exp_f32_e32 v76, v76
	v_exp_f32_e32 v77, v77
	v_exp_f32_e32 v78, v78
	v_mfma_f32_32x32x16_bf16 v[0:15], v[240:243], v[84:87], v[0:15]
	v_exp_f32_e32 v79, v79
	v_add_f32_e32 v208, v72, v208
	v_add_f32_e32 v209, v73, v209
	v_add_f32_e32 v208, v74, v208
	v_add_f32_e32 v209, v75, v209
	v_add_f32_e32 v208, v76, v208
	v_add_f32_e32 v209, v77, v209
	v_add_f32_e32 v208, v78, v208
	v_add_f32_e32 v209, v79, v209
	v_cvt_pk_bf16_f32 v64, v72, v73
	v_cvt_pk_bf16_f32 v65, v74, v75
	v_cvt_pk_bf16_f32 v66, v76, v77
	v_cvt_pk_bf16_f32 v67, v78, v79
	v_add_f32_e32 v211, v208, v209
	v_add_f32_e32 v212, v200, v211
	v_mfma_f32_32x32x16_bf16 v[16:31], v[244:247], v[64:67], v[16:31]
	s_and_b64 vcc, exec, s[8:9]
	s_cbranch_vccz .Lcc_nomaskB
; DI int crow(int reg, int h) { return (reg & 3) + 8 * (reg >> 2) + 4 * h; }
; template <int MODE>
; DI void attn_mfma(const Params& p, int l, int b, int hd, int qb, unsigned char* smem) {
;     ...
;     if (MODE == 1 && j + hf >= 4) {
;       const int iq = tq - NCTX;
;       const int jb = tbcur - NCTX;
; #pragma unroll
;       for (int mt = 0; mt < 2; ++mt)
; #pragma unroll
;         for (int i = 0; i < 16; ++i) {
;           const int dd = iq - (jb + mt * 32 + crow(i, h2));
;           if (dd > 128 || dd < -128) S[mt][i] = -1e30f;
;         }
;     }
	v_add_u32_e32 v168, 0xffffff3f, v201
	v_cmp_lt_u32_e32 vcc, s25, v168
	v_add_u32_e32 v168, 0xc1, v202
	s_nop 0
	v_cndmask_b32_e32 v48, v195, v48, vcc
	v_cmp_gt_u32_e32 vcc, s26, v168
	v_add_u32_e32 v168, 0xffffff3d, v201
	s_nop 0
	v_cndmask_b32_e32 v49, v195, v49, vcc
	v_cmp_lt_u32_e32 vcc, s25, v168
	v_add_u32_e32 v168, 0xffffff3c, v201
	s_nop 0
	v_cndmask_b32_e32 v50, v195, v50, vcc
	v_cmp_lt_u32_e32 vcc, s25, v168
	v_add_u32_e32 v168, 0xffffff37, v201
	s_nop 0
	v_cndmask_b32_e32 v51, v195, v51, vcc
	v_cmp_lt_u32_e32 vcc, s25, v168
	v_add_u32_e32 v168, 0xffffff36, v201
	s_nop 0
	v_cndmask_b32_e32 v52, v195, v52, vcc
	v_cmp_lt_u32_e32 vcc, s25, v168
	v_add_u32_e32 v168, 0xffffff35, v201
	s_nop 0
	v_cndmask_b32_e32 v53, v195, v53, vcc
	v_cmp_lt_u32_e32 vcc, s25, v168
	v_add_u32_e32 v168, 0xffffff34, v201
	s_nop 0
	v_cndmask_b32_e32 v54, v195, v54, vcc
	v_cmp_lt_u32_e32 vcc, s25, v168
	v_add_u32_e32 v168, 0xffffff2f, v201
	s_nop 0
	v_cndmask_b32_e32 v55, v195, v55, vcc
	v_cmp_lt_u32_e32 vcc, s25, v168
	v_add_u32_e32 v168, 0xffffff2e, v201
	s_nop 0
	v_cndmask_b32_e32 v56, v195, v56, vcc
	v_cmp_lt_u32_e32 vcc, s25, v168
	v_add_u32_e32 v168, 0xffffff2d, v201
	s_nop 0
	v_cndmask_b32_e32 v57, v195, v57, vcc
	v_cmp_lt_u32_e32 vcc, s25, v168
	v_add_u32_e32 v168, 0xffffff2c, v201
	s_nop 0
	v_cndmask_b32_e32 v58, v195, v58, vcc
	v_cmp_lt_u32_e32 vcc, s25, v168
	v_add_u32_e32 v168, 0xffffff27, v201
	s_nop 0
	v_cndmask_b32_e32 v59, v195, v59, vcc
	v_cmp_lt_u32_e32 vcc, s25, v168
	v_add_u32_e32 v168, 0xffffff26, v201
	s_nop 0
	v_cndmask_b32_e32 v60, v195, v60, vcc
	v_cmp_lt_u32_e32 vcc, s25, v168
	v_add_u32_e32 v168, 0xffffff25, v201
	s_nop 0
	v_cndmask_b32_e32 v61, v195, v61, vcc
	v_cmp_lt_u32_e32 vcc, s25, v168
	v_add_u32_e32 v168, 0xffffff24, v201
	s_nop 0
	v_cndmask_b32_e32 v62, v195, v62, vcc
	v_cmp_lt_u32_e32 vcc, s25, v168
	v_add_u32_e32 v168, 0xffffff1f, v201
	s_nop 0
	v_cndmask_b32_e32 v63, v195, v63, vcc
	v_cmp_lt_u32_e32 vcc, s25, v168
	v_add_u32_e32 v168, 0xffffff1e, v201
	s_nop 0
	v_cndmask_b32_e32 v32, v195, v32, vcc
	v_cmp_lt_u32_e32 vcc, s25, v168
	v_add_u32_e32 v168, 0xffffff1d, v201
	s_nop 0
	v_cndmask_b32_e32 v33, v195, v33, vcc
	v_cmp_lt_u32_e32 vcc, s25, v168
	v_add_u32_e32 v168, 0xffffff1c, v201
	s_nop 0
	v_cndmask_b32_e32 v34, v195, v34, vcc
	v_cmp_lt_u32_e32 vcc, s25, v168
	v_add_u32_e32 v168, 0xffffff17, v201
	s_nop 0
	v_cndmask_b32_e32 v35, v195, v35, vcc
	v_cmp_lt_u32_e32 vcc, s25, v168
	v_add_u32_e32 v168, 0xffffff16, v201
	s_nop 0
	v_cndmask_b32_e32 v36, v195, v36, vcc
	v_cmp_lt_u32_e32 vcc, s25, v168
	v_add_u32_e32 v168, 0xffffff15, v201
	s_nop 0
	v_cndmask_b32_e32 v37, v195, v37, vcc
	v_cmp_lt_u32_e32 vcc, s25, v168
	v_add_u32_e32 v168, 0xffffff14, v201
	s_nop 0
	v_cndmask_b32_e32 v38, v195, v38, vcc
	v_cmp_lt_u32_e32 vcc, s25, v168
	v_add_u32_e32 v168, 0xffffff0f, v201
	s_nop 0
	v_cndmask_b32_e32 v39, v195, v39, vcc
	v_cmp_lt_u32_e32 vcc, s25, v168
	v_add_u32_e32 v168, 0xffffff0e, v201
	s_nop 0
	v_cndmask_b32_e32 v40, v195, v40, vcc
	v_cmp_lt_u32_e32 vcc, s25, v168
	v_add_u32_e32 v168, 0xffffff0d, v201
	s_nop 0
	v_cndmask_b32_e32 v41, v195, v41, vcc
	v_cmp_lt_u32_e32 vcc, s25, v168
	v_add_u32_e32 v168, 0xffffff0c, v201
	s_nop 0
	v_cndmask_b32_e32 v42, v195, v42, vcc
	v_cmp_lt_u32_e32 vcc, s25, v168
	v_add_u32_e32 v168, 0xffffff07, v201
	s_nop 0
	v_cndmask_b32_e32 v43, v195, v43, vcc
	v_cmp_lt_u32_e32 vcc, s25, v168
	v_add_u32_e32 v168, 0xffffff06, v201
	s_nop 0
	v_cndmask_b32_e32 v44, v195, v44, vcc
	v_cmp_lt_u32_e32 vcc, s25, v168
	v_add_u32_e32 v168, 0xffffff05, v201
	s_nop 0
	v_cndmask_b32_e32 v45, v195, v45, vcc
	v_cmp_lt_u32_e32 vcc, s25, v168
	v_add_u32_e32 v168, 0xffffff04, v201
	s_nop 0
	v_cndmask_b32_e32 v46, v195, v46, vcc
	v_cmp_lt_u32_e32 vcc, s25, v168
	s_nop 1
	v_cndmask_b32_e32 v47, v195, v47, vcc

; DI unsigned pk2(float a, float b) { hwf32x2 f = {a, b}; hwbf16x2 r = __builtin_convertvector(f, hwbf16x2); return __builtin_bit_cast(unsigned, r); }
; #define MFMA32(a, b, c) __builtin_amdgcn_mfma_f32_32x32x16_bf16((a), (b), (c), 0, 0, 0)
; template <int MODE>
; DI void attn_mfma(const Params& p, int l, int b, int hd, int qb, unsigned char* smem) {
;     ...
;     const f32x2 c2 = {cexp, cexp}, m2 = {mrun, mrun};
;     f32x2 ps2 = {0.f, 0.f};
;     unsigned pk[2][8];
; #pragma unroll
;     for (int mt = 0; mt < 2; ++mt)
; #pragma unroll
;       for (int i = 0; i < 8; ++i) {
;         f32x2 z = {S[mt][2 * i], S[mt][2 * i + 1]};
;         z = z * c2 - m2;
;         f32x2 pv = {__builtin_amdgcn_exp2f(z.x), __builtin_amdgcn_exp2f(z.y)};
;         ps2 = ps2 + pv;
;         pk[mt][i] = pk2(pv.x, pv.y);
;       }
;     lsum += ps2.x + ps2.y;
; #pragma unroll
;     for (int mt = 0; mt < 2; ++mt)
; #pragma unroll
;       for (int s = 0; s < 2; ++s) {
;         const uint4 pu = make_uint4(pk[mt][4 * s], pk[mt][4 * s + 1], pk[mt][4 * s + 2], pk[mt][4 * s + 3]);
;         const bf16x8 pf = __builtin_bit_cast(bf16x8, pu);
; #pragma unroll
;         for (int vt = 0; vt < 2; ++vt) {
;           const unsigned char* bp = sVc + (vt * 32 + r) * 136 + (mt * 32 + 16 * s + 4 * h2) * 2;
;           const uint2 lo = *(const uint2*)(bp);
;           const uint2 hi = *(const uint2*)(bp + 16);
;           const uint4 u = make_uint4(lo.x, lo.y, hi.x, hi.y);
;           O[vt] = MFMA32(__builtin_bit_cast(bf16x8, u), pf, O[vt]);
;         }
;       }
;     }
;   }
.Lcc_nrb:
	v_fma_f32 v48, v48, s28, -v166
	v_fma_f32 v49, v49, s28, -v166
	v_fma_f32 v50, v50, s28, -v166
	v_fma_f32 v51, v51, s28, -v166
	v_fma_f32 v52, v52, s28, -v166
	v_fma_f32 v53, v53, s28, -v166
	v_fma_f32 v54, v54, s28, -v166
	v_fma_f32 v55, v55, s28, -v166
	v_exp_f32_e32 v48, v48
	v_exp_f32_e32 v49, v49
	v_exp_f32_e32 v50, v50
	v_exp_f32_e32 v51, v51
	v_exp_f32_e32 v52, v52
	v_exp_f32_e32 v53, v53
	v_exp_f32_e32 v54, v54
	v_exp_f32_e32 v55, v55
	v_add_f32_e32 v208, v50, v48
	v_add_f32_e32 v209, v51, v49
	v_add_f32_e32 v208, v52, v208
	v_add_f32_e32 v209, v53, v209
	v_add_f32_e32 v208, v54, v208
	v_add_f32_e32 v209, v55, v209
	v_cvt_pk_bf16_f32 v48, v48, v49
	v_cvt_pk_bf16_f32 v49, v50, v51
	v_cvt_pk_bf16_f32 v50, v52, v53
	v_cvt_pk_bf16_f32 v51, v54, v55
	v_fma_f32 v56, v56, s28, -v166
	v_fma_f32 v57, v57, s28, -v166
	v_fma_f32 v58, v58, s28, -v166
	s_waitcnt lgkmcnt(4)
	v_mfma_f32_32x32x16_bf16 v[16:31], v[220:223], v[48:51], v[16:31]
	v_fma_f32 v59, v59, s28, -v166
	v_fma_f32 v60, v60, s28, -v166
	v_fma_f32 v61, v61, s28, -v166
	v_fma_f32 v62, v62, s28, -v166
	v_fma_f32 v63, v63, s28, -v166
	v_exp_f32_e32 v56, v56
	v_exp_f32_e32 v57, v57
	v_exp_f32_e32 v58, v58
	v_exp_f32_e32 v59, v59
	v_exp_f32_e32 v60, v60
	v_exp_f32_e32 v61, v61
	v_exp_f32_e32 v62, v62
	v_mfma_f32_32x32x16_bf16 v[0:15], v[224:227], v[48:51], v[0:15]
	v_exp_f32_e32 v63, v63
	v_add_f32_e32 v208, v56, v208
	v_add_f32_e32 v209, v57, v209
	v_add_f32_e32 v208, v58, v208
	v_add_f32_e32 v209, v59, v209
	v_add_f32_e32 v208, v60, v208
	v_add_f32_e32 v209, v61, v209
	v_add_f32_e32 v208, v62, v208
	v_add_f32_e32 v209, v63, v209
	v_cvt_pk_bf16_f32 v56, v56, v57
	v_cvt_pk_bf16_f32 v57, v58, v59
	v_cvt_pk_bf16_f32 v58, v60, v61
	v_cvt_pk_bf16_f32 v59, v62, v63
	v_fma_f32 v32, v32, s28, -v166
	v_fma_f32 v33, v33, s28, -v166
	v_fma_f32 v34, v34, s28, -v166
	v_mfma_f32_32x32x16_bf16 v[16:31], v[228:231], v[56:59], v[16:31]
	v_fma_f32 v35, v35, s28, -v166
	v_fma_f32 v36, v36, s28, -v166
	v_fma_f32 v37, v37, s28, -v166
	v_fma_f32 v38, v38, s28, -v166
	v_fma_f32 v39, v39, s28, -v166
	v_exp_f32_e32 v32, v32
	v_exp_f32_e32 v33, v33
	v_exp_f32_e32 v34, v34
	v_exp_f32_e32 v35, v35
	v_exp_f32_e32 v36, v36
	v_exp_f32_e32 v37, v37
	v_exp_f32_e32 v38, v38
	v_mfma_f32_32x32x16_bf16 v[0:15], v[232:235], v[56:59], v[0:15]
	v_exp_f32_e32 v39, v39
	v_add_f32_e32 v208, v32, v208
	v_add_f32_e32 v209, v33, v209
	v_add_f32_e32 v208, v34, v208
	v_add_f32_e32 v209, v35, v209
	v_add_f32_e32 v208, v36, v208
	v_add_f32_e32 v209, v37, v209
	v_add_f32_e32 v208, v38, v208
	v_add_f32_e32 v209, v39, v209
	v_cvt_pk_bf16_f32 v52, v32, v33
	v_cvt_pk_bf16_f32 v53, v34, v35
	v_cvt_pk_bf16_f32 v54, v36, v37
	v_cvt_pk_bf16_f32 v55, v38, v39
	v_fma_f32 v40, v40, s28, -v166
	v_fma_f32 v41, v41, s28, -v166
	v_fma_f32 v42, v42, s28, -v166
	s_waitcnt lgkmcnt(0)
	v_mfma_f32_32x32x16_bf16 v[16:31], v[236:239], v[52:55], v[16:31]
	v_fma_f32 v43, v43, s28, -v166
	v_fma_f32 v44, v44, s28, -v166
	v_fma_f32 v45, v45, s28, -v166
	v_fma_f32 v46, v46, s28, -v166
	v_fma_f32 v47, v47, s28, -v166
	v_exp_f32_e32 v40, v40
	v_exp_f32_e32 v41, v41
	v_exp_f32_e32 v42, v42
	v_exp_f32_e32 v43, v43
	v_exp_f32_e32 v44, v44
	v_exp_f32_e32 v45, v45
	v_exp_f32_e32 v46, v46
	v_mfma_f32_32x32x16_bf16 v[0:15], v[240:243], v[52:55], v[0:15]
	v_exp_f32_e32 v47, v47
	v_add_f32_e32 v208, v40, v208
	v_add_f32_e32 v209, v41, v209
	v_add_f32_e32 v208, v42, v208
	v_add_f32_e32 v209, v43, v209
	v_add_f32_e32 v208, v44, v208
	v_add_f32_e32 v209, v45, v209
	v_add_f32_e32 v208, v46, v208
	v_add_f32_e32 v209, v47, v209
	v_cvt_pk_bf16_f32 v32, v40, v41
	v_cvt_pk_bf16_f32 v33, v42, v43
	v_cvt_pk_bf16_f32 v34, v44, v45
	v_cvt_pk_bf16_f32 v35, v46, v47
	v_add_f32_e32 v211, v208, v209
	v_add_f32_e32 v200, v212, v211
	v_mfma_f32_32x32x16_bf16 v[16:31], v[244:247], v[32:35], v[16:31]
	s_addk_i32 s19, 0xff80
	v_add_u32_e32 v197, 0x80, v197
	s_addk_i32 s18, 0x80
	v_mfma_f32_32x32x16_bf16 v[0:15], v[248:251], v[32:35], v[0:15]
	s_andn2_b64 vcc, exec, s[6:7]
	s_cbranch_vccz .LBB0_828
	s_mov_b32 s21, s20
	s_branch .LBB0_814
